# combined: packed SwiGLU epilogue + attention tile bases in SGPRs + segment totals preloaded + balanced prologue conversion + two x rows per trip
# speedup vs baseline: 1.0050x; 1.0050x over previous
; __device__ __forceinline__ unsigned pk2(float lo, float hi) { return f2bf(lo) | (f2bf(hi) << 16); }
; __device__ __forceinline__ void row_to_bf16_ssq(const float* xrow, bf16* orow, float* ssq_out, int lane) {
;     const f32x4* xr = (const f32x4*)xrow + lane; f32x4 v[4]; float s2 = 0.f;
; #pragma unroll
;     for (int j = 0; j < 4; ++j) { v[j] = xr[64 * j]; s2 += (v[j].x * v[j].x + v[j].y * v[j].y) + (v[j].z * v[j].z + v[j].w * v[j].w); }
;     s2 = wave_sum(s2);
;     unsigned long long* o8 = (unsigned long long*)orow + lane;
; #pragma unroll
;     for (int j = 0; j < 4; ++j) o8[64 * j] = (unsigned long long)pk2(v[j].x, v[j].y) | ((unsigned long long)pk2(v[j].z, v[j].w) << 32);
;     if (lane < 16) ssq_out[lane] = lane == 0 ? s2 : 0.f;
; }
; __global__ void __launch_bounds__(512, 2) mega_fwd(Args a) {
;     ...
;         for (int m = gw; m < M; m += NGW) row_to_bf16_ssq(x + (size_t)m * D, hb + (size_t)m * D, ssq + (size_t)m * 16, lane);
.LBB0_491:
	s_add_i32 s18, s16, s76
	s_cmpk_gt_i32 s18, 0x3fff
	s_cbranch_scc1 .Lxr_single
	global_load_dwordx4 v[20:23], v[10:11], off offset:-2048
	global_load_dwordx4 v[24:27], v[10:11], off offset:-1024
	global_load_dwordx4 v[28:31], v[10:11], off
	global_load_dwordx4 v[32:35], v[10:11], off offset:1024
	v_lshl_add_u64 v[178:179], v[10:11], 0, s[10:11]
	s_nop 0
	global_load_dwordx4 v[140:143], v[178:179], off offset:-2048
	global_load_dwordx4 v[144:147], v[178:179], off offset:-1024
	global_load_dwordx4 v[148:151], v[178:179], off
	global_load_dwordx4 v[152:155], v[178:179], off offset:1024
	v_lshl_add_u64 v[36:37], s[62:63], 0, v[8:9]
	v_add_co_u32_e64 v36, s[0:1], s13, v36
	s_waitcnt vmcnt(7)
	v_mul_f32_e32 v3, v21, v21
	s_waitcnt lgkmcnt(0)
	v_mul_f32_e32 v5, v23, v23
	s_waitcnt vmcnt(6)
	v_mul_f32_e32 v19, v25, v25
	v_mul_f32_e32 v38, v27, v27
	s_waitcnt vmcnt(5)
	v_mul_f32_e32 v39, v29, v29
	v_mul_f32_e32 v40, v31, v31
	v_fmac_f32_e32 v3, v20, v20
	v_fmac_f32_e32 v5, v22, v22
	v_fmac_f32_e32 v19, v24, v24
	v_fmac_f32_e32 v38, v26, v26
	s_waitcnt vmcnt(4)
	v_mul_f32_e32 v41, v33, v33
	v_mul_f32_e32 v42, v35, v35
	v_fmac_f32_e32 v39, v28, v28
	v_fmac_f32_e32 v40, v30, v30
	v_add_f32_e32 v3, v3, v5
	v_add_f32_e32 v5, v19, v38
	v_fmac_f32_e32 v41, v32, v32
	v_fmac_f32_e32 v42, v34, v34
	v_add_f32_e32 v19, v39, v40
	v_add_f32_e32 v3, v3, v5
	v_add_f32_e32 v38, v41, v42
	v_add_f32_e32 v3, v3, v19
	v_add_f32_e32 v3, v3, v38
	ds_bpermute_b32 v5, v13, v3
	v_bfe_u32 v43, v20, 16, 1
	v_bfe_u32 v45, v22, 16, 1
	v_bfe_u32 v44, v21, 16, 1
	v_bfe_u32 v46, v23, 16, 1
	s_waitcnt lgkmcnt(0)
	v_add_f32_e32 v3, v3, v5
	ds_bpermute_b32 v5, v14, v3
	v_bfe_u32 v47, v24, 16, 1
	v_bfe_u32 v49, v26, 16, 1
	v_bfe_u32 v51, v28, 16, 1
	v_bfe_u32 v53, v30, 16, 1
	s_waitcnt lgkmcnt(0)
	v_add_f32_e32 v3, v3, v5
	ds_bpermute_b32 v5, v15, v3
	v_add3_u32 v20, v20, v43, s5
	v_add3_u32 v22, v22, v45, s5
	v_bfe_u32 v48, v25, 16, 1
	v_bfe_u32 v50, v27, 16, 1
	s_waitcnt lgkmcnt(0)
	v_add_f32_e32 v3, v3, v5
	ds_bpermute_b32 v5, v16, v3
	v_bfe_u32 v52, v29, 16, 1
	v_bfe_u32 v54, v31, 16, 1
	v_bfe_u32 v55, v32, 16, 1
	v_add3_u32 v21, v21, v44, s5
	s_waitcnt lgkmcnt(0)
	v_add_f32_e32 v3, v3, v5
	ds_bpermute_b32 v5, v17, v3
	v_add3_u32 v23, v23, v46, s5
	v_add3_u32 v24, v24, v47, s5
	v_add3_u32 v26, v26, v49, s5
	v_add3_u32 v28, v28, v51, s5
	s_waitcnt lgkmcnt(0)
	v_add_f32_e32 v3, v3, v5
	v_add3_u32 v30, v30, v53, s5
	v_lshrrev_b32_e32 v20, 16, v20
	v_lshrrev_b32_e32 v22, 16, v22
	ds_bpermute_b32 v5, v18, v3
	v_addc_co_u32_e64 v37, s[0:1], 0, v37, s[0:1]
	v_bfe_u32 v56, v33, 16, 1
	v_bfe_u32 v57, v34, 16, 1
	v_add3_u32 v25, v25, v48, s5
	v_add3_u32 v27, v27, v50, s5
	v_add3_u32 v29, v29, v52, s5
	v_add3_u32 v31, v31, v54, s5
	v_add3_u32 v19, v32, v55, s5
	v_lshrrev_b32_e32 v24, 16, v24
	v_lshrrev_b32_e32 v26, 16, v26
	v_lshrrev_b32_e32 v28, 16, v28
	v_lshrrev_b32_e32 v30, 16, v30
	v_and_or_b32 v20, v21, s12, v20
	v_and_or_b32 v21, v23, s12, v22
	v_add3_u32 v32, v33, v56, s5
	v_add3_u32 v33, v34, v57, s5
	v_lshrrev_b32_e32 v19, 16, v19
	v_and_or_b32 v22, v25, s12, v24
	v_and_or_b32 v23, v27, s12, v26
	v_and_or_b32 v24, v29, s12, v28
	v_and_or_b32 v25, v31, s12, v30
	global_store_dwordx2 v[36:37], v[20:21], off
	global_store_dwordx2 v[36:37], v[22:23], off offset:512
	global_store_dwordx2 v[36:37], v[24:25], off offset:1024
	v_bfe_u32 v20, v35, 16, 1
	v_and_or_b32 v26, v32, s12, v19
	v_lshrrev_b32_e32 v19, 16, v33
	v_add3_u32 v20, v35, v20, s5
	v_and_or_b32 v27, v20, s12, v19
	global_store_dwordx2 v[36:37], v[26:27], off offset:1536
	s_and_saveexec_b64 s[0:1], vcc
	s_cbranch_execz .Lxr_a
	s_waitcnt lgkmcnt(0)
	v_add_f32_e32 v3, v3, v5
	v_cndmask_b32_e64 v3, 0, v3, s[2:3]
	v_lshl_add_u64 v[20:21], s[62:63], 0, v[6:7]
	global_store_dword v[20:21], v3, off
; __device__ __forceinline__ unsigned pk2(float lo, float hi) { return f2bf(lo) | (f2bf(hi) << 16); }
; __device__ __forceinline__ void row_to_bf16_ssq(const float* xrow, bf16* orow, float* ssq_out, int lane) {
;     const f32x4* xr = (const f32x4*)xrow + lane; f32x4 v[4]; float s2 = 0.f;
; #pragma unroll
;     for (int j = 0; j < 4; ++j) { v[j] = xr[64 * j]; s2 += (v[j].x * v[j].x + v[j].y * v[j].y) + (v[j].z * v[j].z + v[j].w * v[j].w); }
;     s2 = wave_sum(s2);
;     unsigned long long* o8 = (unsigned long long*)orow + lane;
; #pragma unroll
;     for (int j = 0; j < 4; ++j) o8[64 * j] = (unsigned long long)pk2(v[j].x, v[j].y) | ((unsigned long long)pk2(v[j].z, v[j].w) << 32);
;     if (lane < 16) ssq_out[lane] = lane == 0 ? s2 : 0.f;
; }
; __global__ void __launch_bounds__(512, 2) mega_fwd(Args a) {
;     ...
;         for (int m = gw; m < M; m += NGW) row_to_bf16_ssq(x + (size_t)m * D, hb + (size_t)m * D, ssq + (size_t)m * 16, lane);
.Lxr_a:
	s_or_b64 exec, exec, s[0:1]
	s_add_i32 s16, s16, s76
	v_lshl_add_u64 v[6:7], v[6:7], 0, s[6:7]
	v_lshl_add_u64 v[8:9], v[8:9], 0, s[8:9]
	v_lshl_add_u64 v[10:11], v[10:11], 0, s[10:11]
	v_lshl_add_u64 v[156:157], s[62:63], 0, v[8:9]
	v_add_co_u32_e64 v156, s[0:1], s13, v156
	s_waitcnt vmcnt(8)
	v_mul_f32_e32 v136, v141, v141
	s_waitcnt lgkmcnt(0)
	v_mul_f32_e32 v137, v143, v143
	s_waitcnt vmcnt(7)
	v_mul_f32_e32 v139, v145, v145
	v_mul_f32_e32 v158, v147, v147
	s_waitcnt vmcnt(6)
	v_mul_f32_e32 v159, v149, v149
	v_mul_f32_e32 v160, v151, v151
	v_fmac_f32_e32 v136, v140, v140
	v_fmac_f32_e32 v137, v142, v142
	v_fmac_f32_e32 v139, v144, v144
	v_fmac_f32_e32 v158, v146, v146
	s_waitcnt vmcnt(5)
	v_mul_f32_e32 v161, v153, v153
	v_mul_f32_e32 v162, v155, v155
	v_fmac_f32_e32 v159, v148, v148
	v_fmac_f32_e32 v160, v150, v150
	v_add_f32_e32 v136, v136, v137
	v_add_f32_e32 v137, v139, v158
	v_fmac_f32_e32 v161, v152, v152
	v_fmac_f32_e32 v162, v154, v154
	v_add_f32_e32 v139, v159, v160
	v_add_f32_e32 v136, v136, v137
	v_add_f32_e32 v158, v161, v162
	v_add_f32_e32 v136, v136, v139
	v_add_f32_e32 v136, v136, v158
	ds_bpermute_b32 v137, v13, v136
	v_bfe_u32 v163, v140, 16, 1
	v_bfe_u32 v165, v142, 16, 1
	v_bfe_u32 v164, v141, 16, 1
	v_bfe_u32 v166, v143, 16, 1
	s_waitcnt lgkmcnt(0)
	v_add_f32_e32 v136, v136, v137
	ds_bpermute_b32 v137, v14, v136
	v_bfe_u32 v167, v144, 16, 1
	v_bfe_u32 v169, v146, 16, 1
	v_bfe_u32 v171, v148, 16, 1
	v_bfe_u32 v173, v150, 16, 1
	s_waitcnt lgkmcnt(0)
	v_add_f32_e32 v136, v136, v137
	ds_bpermute_b32 v137, v15, v136
	v_add3_u32 v140, v140, v163, s5
	v_add3_u32 v142, v142, v165, s5
	v_bfe_u32 v168, v145, 16, 1
	v_bfe_u32 v170, v147, 16, 1
	s_waitcnt lgkmcnt(0)
	v_add_f32_e32 v136, v136, v137
	ds_bpermute_b32 v137, v16, v136
	v_bfe_u32 v172, v149, 16, 1
	v_bfe_u32 v174, v151, 16, 1
	v_bfe_u32 v175, v152, 16, 1
	v_add3_u32 v141, v141, v164, s5
	s_waitcnt lgkmcnt(0)
	v_add_f32_e32 v136, v136, v137
	ds_bpermute_b32 v137, v17, v136
	v_add3_u32 v143, v143, v166, s5
	v_add3_u32 v144, v144, v167, s5
	v_add3_u32 v146, v146, v169, s5
	v_add3_u32 v148, v148, v171, s5
	s_waitcnt lgkmcnt(0)
	v_add_f32_e32 v136, v136, v137
	v_add3_u32 v150, v150, v173, s5
	v_lshrrev_b32_e32 v140, 16, v140
	v_lshrrev_b32_e32 v142, 16, v142
	ds_bpermute_b32 v137, v18, v136
	v_addc_co_u32_e64 v157, s[0:1], 0, v157, s[0:1]
	v_bfe_u32 v176, v153, 16, 1
	v_bfe_u32 v177, v154, 16, 1
	v_add3_u32 v145, v145, v168, s5
	v_add3_u32 v147, v147, v170, s5
	v_add3_u32 v149, v149, v172, s5
	v_add3_u32 v151, v151, v174, s5
	v_add3_u32 v139, v152, v175, s5
	v_lshrrev_b32_e32 v144, 16, v144
	v_lshrrev_b32_e32 v146, 16, v146
	v_lshrrev_b32_e32 v148, 16, v148
	v_lshrrev_b32_e32 v150, 16, v150
	v_and_or_b32 v140, v141, s12, v140
	v_and_or_b32 v141, v143, s12, v142
	v_add3_u32 v152, v153, v176, s5
	v_add3_u32 v153, v154, v177, s5
	v_lshrrev_b32_e32 v139, 16, v139
	v_and_or_b32 v142, v145, s12, v144
	v_and_or_b32 v143, v147, s12, v146
	v_and_or_b32 v144, v149, s12, v148
	v_and_or_b32 v145, v151, s12, v150
	global_store_dwordx2 v[156:157], v[140:141], off
	global_store_dwordx2 v[156:157], v[142:143], off offset:512
	global_store_dwordx2 v[156:157], v[144:145], off offset:1024
	v_bfe_u32 v140, v155, 16, 1
	v_and_or_b32 v146, v152, s12, v139
	v_lshrrev_b32_e32 v139, 16, v153
	v_add3_u32 v140, v155, v140, s5
	v_and_or_b32 v147, v140, s12, v139
	global_store_dwordx2 v[156:157], v[146:147], off offset:1536
	s_and_saveexec_b64 s[0:1], vcc
	s_cbranch_execz .Lxr_b
	s_waitcnt lgkmcnt(0)
	v_add_f32_e32 v136, v136, v137
	v_cndmask_b32_e64 v136, 0, v136, s[2:3]
	v_lshl_add_u64 v[140:141], s[62:63], 0, v[6:7]
	global_store_dword v[140:141], v136, off
.Lxr_b:
	s_or_b64 exec, exec, s[0:1]
	s_add_i32 s16, s16, s76
	v_lshl_add_u64 v[6:7], v[6:7], 0, s[6:7]
	v_lshl_add_u64 v[8:9], v[8:9], 0, s[8:9]
	v_lshl_add_u64 v[10:11], v[10:11], 0, s[10:11]
	s_cmpk_gt_i32 s16, 0x3fff
	s_cbranch_scc1 .LBB0_493
	s_branch .LBB0_491
